# v23 + the first score block's bf16 pack also moved into the PV phase (after its exp/sum)
# baseline (speedup 1.0000x reference)
.LBB0_1038:
	s_or_b64 exec, exec, s[4:5]
	v_and_b32_e32 v0, 0x60, v26
	s_movk_i32 s4, 0x90
	v_lshlrev_b32_e32 v2, 3, v32
	v_mad_u32_u24 v207, v203, s4, 0
	v_mad_u64_u32 v[0:1], s[4:5], v28, s4, v[0:1]
	v_and_or_b32 v0, v2, 8, v0
	v_lshlrev_b32_e32 v1, 6, v203
	v_add_u32_e32 v208, 0, v0
	v_add3_u32 v204, v207, v1, v184
	v_add_u32_e32 v1, 0, v4
	v_add_u32_e32 v205, 0x9800, v208
	s_waitcnt vmcnt(3)
	ds_write_b128 v1, v[8:11] offset:13312
	s_waitcnt vmcnt(2)
	ds_write2_b64 v205, v[16:17], v[18:19] offset0:128 offset1:130
	s_waitcnt lgkmcnt(0)
	s_barrier
	ds_read_b128 v[0:3], v204
	ds_read_b128 v[4:7], v204 offset:32
	ds_read_b128 v[8:11], v204 offset:6656
	ds_read_b128 v[12:15], v204 offset:6688
	ds_read_b128 v[16:19], v204 offset:64
	ds_read_b128 v[28:31], v204 offset:96
	ds_read_b128 v[64:67], v204 offset:6720
	ds_read_b128 v[68:71], v204 offset:6752
	ds_read_b128 v[72:75], v204 offset:128
	ds_read_b128 v[76:79], v204 offset:160
	ds_read_b128 v[80:83], v204 offset:6784
	ds_read_b128 v[84:87], v204 offset:6816
	s_mov_b32 s91, 2
	s_lshl_b32 s87, s6, 2
	s_waitcnt lgkmcnt(11)
	v_mfma_f32_32x32x16_bf16 v[48:63], v[0:3], v[100:103], 0
	s_mov_b32 s79, 0
	s_waitcnt lgkmcnt(9)
	v_mfma_f32_32x32x16_bf16 v[32:47], v[8:11], v[100:103], 0
	v_mfma_f32_32x32x16_bf16 v[48:63], v[4:7], v[104:107], v[48:63]
	s_waitcnt lgkmcnt(8)
	v_mfma_f32_32x32x16_bf16 v[32:47], v[12:15], v[104:107], v[32:47]
	s_waitcnt lgkmcnt(7)
	v_mfma_f32_32x32x16_bf16 v[48:63], v[16:19], v[108:111], v[48:63]
	s_waitcnt lgkmcnt(5)
	v_mfma_f32_32x32x16_bf16 v[32:47], v[64:67], v[108:111], v[32:47]
	v_mfma_f32_32x32x16_bf16 v[48:63], v[28:31], v[112:115], v[48:63]
	s_waitcnt lgkmcnt(4)
	v_mfma_f32_32x32x16_bf16 v[32:47], v[68:71], v[112:115], v[32:47]
	s_waitcnt lgkmcnt(3)
	v_mfma_f32_32x32x16_bf16 v[48:63], v[72:75], v[116:119], v[48:63]
	s_waitcnt lgkmcnt(1)
	v_mfma_f32_32x32x16_bf16 v[32:47], v[80:83], v[116:119], v[32:47]
	v_mfma_f32_32x32x16_bf16 v[48:63], v[76:79], v[120:123], v[48:63]
	s_waitcnt lgkmcnt(0)
	v_mfma_f32_32x32x16_bf16 v[32:47], v[84:87], v[120:123], v[32:47]
	ds_read_b128 v[172:175], v204 offset:13312
	ds_read_b128 v[152:155], v204 offset:13344
	ds_read_b128 v[180:183], v204 offset:19968
	ds_read_b128 v[164:167], v204 offset:20000
	ds_read_b128 v[156:159], v204 offset:13376
	ds_read_b128 v[140:143], v204 offset:13408
	ds_read_b128 v[176:179], v204 offset:20032
	ds_read_b128 v[160:163], v204 offset:20064
	ds_read_b128 v[148:151], v204 offset:13440
	ds_read_b128 v[136:139], v204 offset:13472
	ds_read_b128 v[168:171], v204 offset:20096
	ds_read_b128 v[144:147], v204 offset:20128
	s_add_u32 s4, s60, 0x100
	v_lshl_add_u64 v[0:1], s[60:61], 0, v[24:25]
	v_mov_b32_e32 v27, v97
	s_addc_u32 s5, 0, 0
	v_lshl_add_u64 v[190:191], v[0:1], 0, v[26:27]
	v_lshl_add_u64 v[0:1], s[4:5], 0, v[24:25]
	v_mov_b32_e32 v199, 0
	v_lshl_add_u64 v[188:189], s[96:97], 0, v[20:21]
	v_lshl_add_u64 v[186:187], s[96:97], 0, v[22:23]
	v_lshl_add_u64 v[98:99], v[0:1], 0, v[26:27]
	s_add_u32 s98, s94, 0x12209000
	s_addc_u32 s99, s95, 0
	s_add_u32 s100, s94, 0x11200000
	s_addc_u32 s101, s95, 0

	v_exp_f32_e32 v48, v48
	v_exp_f32_e32 v49, v49
	v_exp_f32_e32 v50, v50
	v_add_f32_e32 v195, v48, v49
	v_exp_f32_e32 v51, v51
	v_add_f32_e32 v195, v50, v195
	v_exp_f32_e32 v52, v52
	v_add_f32_e32 v195, v51, v195
	v_exp_f32_e32 v53, v53
	v_add_f32_e32 v195, v52, v195
	v_exp_f32_e32 v54, v54
	v_add_f32_e32 v195, v53, v195
	v_exp_f32_e32 v55, v55
	v_add_f32_e32 v195, v54, v195
	v_exp_f32_e32 v56, v56
	v_add_f32_e32 v195, v55, v195
	v_exp_f32_e32 v57, v57
	v_add_f32_e32 v195, v56, v195
	v_exp_f32_e32 v58, v58
	v_add_f32_e32 v195, v57, v195
	v_exp_f32_e32 v59, v59
	v_add_f32_e32 v195, v58, v195
	v_exp_f32_e32 v60, v60
	v_add_f32_e32 v195, v59, v195
	v_exp_f32_e32 v61, v61
	v_add_f32_e32 v195, v60, v195
	v_exp_f32_e32 v62, v62
	v_add_f32_e32 v195, v61, v195
	v_exp_f32_e32 v63, v63
	v_add_f32_e32 v195, v62, v195
	v_add_f32_e32 v195, v63, v195
	v_cvt_pk_bf16_f32 v48, v48, v49
	v_cvt_pk_bf16_f32 v49, v50, v51
	v_cvt_pk_bf16_f32 v50, v52, v53
	v_cvt_pk_bf16_f32 v51, v54, v55
	v_cvt_pk_bf16_f32 v52, v56, v57
	v_cvt_pk_bf16_f32 v53, v58, v59
	v_cvt_pk_bf16_f32 v54, v60, v61
	v_cvt_pk_bf16_f32 v55, v62, v63
	s_movk_i32 s93, 0xbf
	v_mov_b32_e32 v0, 0
	v_mov_b32_e32 v1, v199
	v_mov_b32_e32 v2, v199
	v_mov_b32_e32 v3, v199
	v_mov_b32_e32 v4, v199
	v_mov_b32_e32 v5, v199
	v_mov_b32_e32 v6, v199
	v_mov_b32_e32 v7, v199
	v_mov_b32_e32 v8, v199
	v_mov_b32_e32 v9, v199
	v_mov_b32_e32 v10, v199
	v_mov_b32_e32 v11, v199
	v_mov_b32_e32 v12, v199
	v_mov_b32_e32 v13, v199
	v_mov_b32_e32 v14, v199
	v_mov_b32_e32 v15, v199
	v_mov_b32_e32 v16, 0
	v_mov_b32_e32 v17, v199
	v_mov_b32_e32 v18, v199
	v_mov_b32_e32 v19, v199
	v_mov_b32_e32 v20, v199
	v_mov_b32_e32 v21, v199
	v_mov_b32_e32 v22, v199
	v_mov_b32_e32 v23, v199
	v_mov_b32_e32 v24, v199
	v_mov_b32_e32 v25, v199
	v_mov_b32_e32 v26, v199
	v_mov_b32_e32 v27, v199
	v_mov_b32_e32 v28, v199
	v_mov_b32_e32 v29, v199
	v_mov_b32_e32 v30, v199
	v_mov_b32_e32 v31, v199
.LBB0_1039:
	s_waitcnt lgkmcnt(11)
	v_mfma_f32_32x32x16_bf16 v[64:79], v[172:175], v[100:103], 0
	v_exp_f32_e32 v32, v32
	v_exp_f32_e32 v33, v33
	s_waitcnt lgkmcnt(9)
	v_mfma_f32_32x32x16_bf16 v[80:95], v[180:183], v[100:103], 0
	v_exp_f32_e32 v34, v34
	v_add_f32_e32 v251, v32, v33
	v_exp_f32_e32 v35, v35
	v_add_f32_e32 v251, v34, v251
	v_mfma_f32_32x32x16_bf16 v[64:79], v[152:155], v[104:107], v[64:79]
	v_exp_f32_e32 v36, v36
	v_add_f32_e32 v251, v35, v251
	v_exp_f32_e32 v37, v37
	s_waitcnt lgkmcnt(8)
	v_mfma_f32_32x32x16_bf16 v[80:95], v[164:167], v[104:107], v[80:95]
	v_add_f32_e32 v251, v36, v251
	v_exp_f32_e32 v38, v38
	v_add_f32_e32 v251, v37, v251
	s_waitcnt lgkmcnt(7)
	v_mfma_f32_32x32x16_bf16 v[64:79], v[156:159], v[108:111], v[64:79]
	v_exp_f32_e32 v39, v39
	v_add_f32_e32 v251, v38, v251
	v_exp_f32_e32 v40, v40
	s_mul_i32 s6, s91, 0x3400
	s_add_i32 s7, s6, 0

	v_add_u32_e32 v253, s7, v96
	s_waitcnt vmcnt(1)
	ds_write_b128 v253, v[128:131]
	s_and_saveexec_b64 s[4:5], s[2:3]
	v_add_u32_e32 v253, s7, v185
	ds_write_b128 v253, v[124:127]
	s_or_b64 exec, exec, s[4:5]
	v_lshl_add_u64 v[200:201], s[100:101], 0, v[190:191]

	v_add_u32_e32 v206, 0xc000, v208
	v_lshl_add_u64 v[128:129], s[98:99], 0, v[188:189]
	s_nop 0
	global_load_dwordx4 v[128:131], v[128:129], off
	s_waitcnt vmcnt(1)
	ds_write2_b64 v206, v[132:133], v[134:135] offset1:2

	s_and_saveexec_b64 s[4:5], s[2:3]
	s_cbranch_execz .LatA_h0
	v_lshl_add_u64 v[124:125], s[98:99], 0, v[186:187]
	s_nop 0
	global_load_dwordx4 v[124:127], v[124:125], off
.LatA_h0:
	s_or_b64 exec, exec, s[4:5]
	global_load_dwordx4 v[132:135], v[200:201], off offset:256

	s_waitcnt lgkmcnt(7)
	v_mfma_f32_32x32x16_bf16 v[80:95], v[176:179], v[108:111], v[80:95]
	v_add_f32_e32 v251, v39, v251
	v_exp_f32_e32 v41, v41
	v_add_f32_e32 v251, v40, v251
	v_mfma_f32_32x32x16_bf16 v[64:79], v[140:143], v[112:115], v[64:79]
	v_exp_f32_e32 v42, v42
	v_add_f32_e32 v251, v41, v251
	v_exp_f32_e32 v43, v43
	s_waitcnt lgkmcnt(6)
	v_mfma_f32_32x32x16_bf16 v[80:95], v[160:163], v[112:115], v[80:95]
	v_add_f32_e32 v251, v42, v251
	v_exp_f32_e32 v44, v44
	v_add_f32_e32 v251, v43, v251
	v_exp_f32_e32 v45, v45
	s_waitcnt lgkmcnt(5)
	v_mfma_f32_32x32x16_bf16 v[64:79], v[148:151], v[116:119], v[64:79]
	v_add_f32_e32 v251, v44, v251
	v_exp_f32_e32 v46, v46
	v_add_f32_e32 v251, v45, v251
	v_add_u32_e32 v198, v207, v184
	ds_read_b128 v[210:213], v198 offset:44544
	ds_read_b128 v[214:217], v198 offset:39936
	ds_read_b128 v[218:221], v198 offset:39968
	ds_read_b128 v[222:225], v198 offset:44576
	ds_read_b128 v[226:229], v198 offset:40000
	ds_read_b128 v[230:233], v198 offset:44608
	ds_read_b128 v[234:237], v198 offset:40032
	ds_read_b128 v[238:241], v198 offset:44640
	s_waitcnt lgkmcnt(11)
	v_mfma_f32_32x32x16_bf16 v[80:95], v[168:171], v[116:119], v[80:95]
	v_exp_f32_e32 v47, v47
	v_add_f32_e32 v251, v46, v251
	v_add_f32_e32 v251, v47, v251
	v_cvt_pk_bf16_f32 v32, v32, v33
	v_mfma_f32_32x32x16_bf16 v[64:79], v[136:139], v[120:123], v[64:79]
	v_cvt_pk_bf16_f32 v33, v34, v35
	v_cvt_pk_bf16_f32 v34, v36, v37
	v_cvt_pk_bf16_f32 v35, v38, v39
	v_cvt_pk_bf16_f32 v36, v40, v41
	s_waitcnt lgkmcnt(10)
	v_mfma_f32_32x32x16_bf16 v[80:95], v[144:147], v[120:123], v[80:95]
	v_cvt_pk_bf16_f32 v37, v42, v43
	v_cvt_pk_bf16_f32 v38, v44, v45
	v_cvt_pk_bf16_f32 v39, v46, v47
	v_add_f32_e32 v195, v195, v251
	v_add_f32_e32 v199, v199, v195
	s_waitcnt lgkmcnt(0)
	s_barrier

	v_add_u32_e32 v197, s6, v204
	s_setprio 1
	v_mfma_f32_32x32x16_bf16 v[0:15], v[48:51], v[210:213], v[0:15]
	ds_read_b128 v[172:175], v197
	ds_read_b128 v[152:155], v197 offset:32
	v_mfma_f32_32x32x16_bf16 v[0:15], v[52:55], v[222:225], v[0:15]
	ds_read_b128 v[180:183], v197 offset:6656
	ds_read_b128 v[164:167], v197 offset:6688
	v_mfma_f32_32x32x16_bf16 v[0:15], v[32:35], v[230:233], v[0:15]
	ds_read_b128 v[156:159], v197 offset:64
	ds_read_b128 v[140:143], v197 offset:96
	v_exp_f32_e32 v64, v64
	v_exp_f32_e32 v65, v65
	v_exp_f32_e32 v66, v66
	v_add_f32_e32 v195, v64, v65
	v_exp_f32_e32 v67, v67
	v_mfma_f32_32x32x16_bf16 v[0:15], v[36:39], v[238:241], v[0:15]
	s_setprio 0
	ds_read_b128 v[176:179], v197 offset:6720
	ds_read_b128 v[160:163], v197 offset:6752
	v_add_f32_e32 v195, v66, v195
	v_exp_f32_e32 v68, v68
	v_add_f32_e32 v195, v67, v195
	v_exp_f32_e32 v69, v69
	v_add_f32_e32 v195, v68, v195
	v_exp_f32_e32 v70, v70
	v_mfma_f32_32x32x16_bf16 v[16:31], v[48:51], v[214:217], v[16:31]
	ds_read_b128 v[148:151], v197 offset:128
	ds_read_b128 v[136:139], v197 offset:160
	v_add_f32_e32 v195, v69, v195
	v_exp_f32_e32 v71, v71
	v_add_f32_e32 v195, v70, v195
	v_exp_f32_e32 v72, v72
	v_add_f32_e32 v195, v71, v195
	v_exp_f32_e32 v73, v73
	v_add_f32_e32 v195, v72, v195
	v_mfma_f32_32x32x16_bf16 v[16:31], v[52:55], v[218:221], v[16:31]
	ds_read_b128 v[168:171], v197 offset:6784
	ds_read_b128 v[144:147], v197 offset:6816
	v_exp_f32_e32 v74, v74
	v_add_f32_e32 v195, v73, v195
	v_exp_f32_e32 v75, v75
	v_add_f32_e32 v195, v74, v195
	v_exp_f32_e32 v76, v76
	v_add_f32_e32 v195, v75, v195
	v_mfma_f32_32x32x16_bf16 v[16:31], v[32:35], v[226:229], v[16:31]
	v_exp_f32_e32 v77, v77
	v_add_f32_e32 v195, v76, v195
	v_exp_f32_e32 v78, v78
	v_add_f32_e32 v195, v77, v195
	v_exp_f32_e32 v79, v79
	v_add_f32_e32 v195, v78, v195
	v_mfma_f32_32x32x16_bf16 v[16:31], v[36:39], v[234:237], v[16:31]
	v_add_f32_e32 v195, v79, v195
	v_cvt_pk_bf16_f32 v64, v64, v65
	v_cvt_pk_bf16_f32 v65, v66, v67
	v_cvt_pk_bf16_f32 v66, v68, v69
	v_cvt_pk_bf16_f32 v67, v70, v71
	v_cvt_pk_bf16_f32 v68, v72, v73
	v_cvt_pk_bf16_f32 v69, v74, v75
	v_cvt_pk_bf16_f32 v70, v76, v77
	v_cvt_pk_bf16_f32 v71, v78, v79
	s_waitcnt lgkmcnt(11)
	v_mfma_f32_32x32x16_bf16 v[48:63], v[172:175], v[100:103], 0
	v_exp_f32_e32 v80, v80
	v_exp_f32_e32 v81, v81
	s_waitcnt lgkmcnt(9)
	v_mfma_f32_32x32x16_bf16 v[32:47], v[180:183], v[100:103], 0
	v_exp_f32_e32 v82, v82
	v_add_f32_e32 v251, v80, v81
	v_exp_f32_e32 v83, v83
	v_add_f32_e32 v251, v82, v251
	v_mfma_f32_32x32x16_bf16 v[48:63], v[152:155], v[104:107], v[48:63]
	v_exp_f32_e32 v84, v84
	v_add_f32_e32 v251, v83, v251
	v_exp_f32_e32 v85, v85
	s_waitcnt lgkmcnt(8)
	v_mfma_f32_32x32x16_bf16 v[32:47], v[164:167], v[104:107], v[32:47]
	v_add_f32_e32 v251, v84, v251
	v_exp_f32_e32 v86, v86
	v_add_f32_e32 v251, v85, v251
	s_waitcnt lgkmcnt(7)
	v_mfma_f32_32x32x16_bf16 v[48:63], v[156:159], v[108:111], v[48:63]
	v_exp_f32_e32 v87, v87
	v_add_f32_e32 v251, v86, v251
	v_exp_f32_e32 v88, v88
	s_add_i32 s4, s91, 1
	s_cmp_lg_u32 s91, 2
	s_cselect_b32 s74, s4, 0
	s_mul_i32 s6, s74, 0x3400
	s_add_i32 s7, s6, 0
	s_add_u32 s98, s98, 0x3000
	s_addc_u32 s99, s99, 0

	v_add_u32_e32 v253, s7, v96
	s_waitcnt vmcnt(1)
	ds_write_b128 v253, v[128:131]
	s_and_saveexec_b64 s[4:5], s[2:3]
	v_add_u32_e32 v253, s7, v185
	ds_write_b128 v253, v[124:127]
	s_or_b64 exec, exec, s[4:5]
	v_lshl_add_u64 v[200:201], s[100:101], 0, v[190:191]

	s_waitcnt vmcnt(0)
	ds_write2_b64 v205, v[132:133], v[134:135] offset0:128 offset1:130
	v_lshl_add_u64 v[128:129], s[98:99], 0, v[188:189]
	s_nop 0
	global_load_dwordx4 v[128:131], v[128:129], off

	s_and_saveexec_b64 s[4:5], s[2:3]
	s_cbranch_execz .LatA_h1
	v_lshl_add_u64 v[124:125], s[98:99], 0, v[186:187]
	s_nop 0
	global_load_dwordx4 v[124:127], v[124:125], off
.LatA_h1:
	s_or_b64 exec, exec, s[4:5]
	global_load_dwordx4 v[132:135], v[200:201], off offset:384

	s_sub_u32 s98, s98, 0x3000
	s_subb_u32 s99, s99, 0

	s_waitcnt lgkmcnt(7)
	v_mfma_f32_32x32x16_bf16 v[32:47], v[176:179], v[108:111], v[32:47]
	v_add_f32_e32 v251, v87, v251
	v_exp_f32_e32 v89, v89
	v_add_f32_e32 v251, v88, v251
	v_mfma_f32_32x32x16_bf16 v[48:63], v[140:143], v[112:115], v[48:63]
	v_exp_f32_e32 v90, v90
	v_add_f32_e32 v251, v89, v251
	v_exp_f32_e32 v91, v91
	s_waitcnt lgkmcnt(6)
	v_mfma_f32_32x32x16_bf16 v[32:47], v[160:163], v[112:115], v[32:47]
	v_add_f32_e32 v251, v90, v251
	v_exp_f32_e32 v92, v92
	v_add_f32_e32 v251, v91, v251
	v_exp_f32_e32 v93, v93
	s_waitcnt lgkmcnt(5)
	v_mfma_f32_32x32x16_bf16 v[48:63], v[148:151], v[116:119], v[48:63]
	v_add_f32_e32 v251, v92, v251
	v_exp_f32_e32 v94, v94
	v_add_f32_e32 v251, v93, v251
	v_add_u32_e32 v198, v207, v184
	ds_read_b128 v[210:213], v198 offset:53760
	ds_read_b128 v[214:217], v198 offset:49152
	ds_read_b128 v[218:221], v198 offset:49184
	ds_read_b128 v[222:225], v198 offset:53792
	ds_read_b128 v[226:229], v198 offset:49216
	ds_read_b128 v[230:233], v198 offset:53824
	ds_read_b128 v[234:237], v198 offset:49248
	ds_read_b128 v[238:241], v198 offset:53856
	s_waitcnt lgkmcnt(11)
	v_mfma_f32_32x32x16_bf16 v[32:47], v[168:171], v[116:119], v[32:47]
	v_exp_f32_e32 v95, v95
	v_add_f32_e32 v251, v94, v251
	v_add_f32_e32 v251, v95, v251
	v_cvt_pk_bf16_f32 v80, v80, v81
	v_mfma_f32_32x32x16_bf16 v[48:63], v[136:139], v[120:123], v[48:63]
	v_cvt_pk_bf16_f32 v81, v82, v83
	v_cvt_pk_bf16_f32 v82, v84, v85
	v_cvt_pk_bf16_f32 v83, v86, v87
	v_cvt_pk_bf16_f32 v84, v88, v89
	s_waitcnt lgkmcnt(10)
	v_mfma_f32_32x32x16_bf16 v[32:47], v[144:147], v[120:123], v[32:47]
	v_cvt_pk_bf16_f32 v85, v90, v91
	v_cvt_pk_bf16_f32 v86, v92, v93
	v_cvt_pk_bf16_f32 v87, v94, v95
	v_add_f32_e32 v195, v195, v251
	v_add_f32_e32 v199, v199, v195
	s_add_i32 s92, s79, 2
	s_waitcnt lgkmcnt(0)
	s_barrier

	s_cmp_ge_u32 s92, s87
	s_cbranch_scc1 .LatA_yplain

	v_add_u32_e32 v197, s6, v204
	s_setprio 1
	v_mfma_f32_32x32x16_bf16 v[0:15], v[64:67], v[210:213], v[0:15]
	ds_read_b128 v[172:175], v197
	ds_read_b128 v[152:155], v197 offset:32
	v_mfma_f32_32x32x16_bf16 v[0:15], v[68:71], v[222:225], v[0:15]
	ds_read_b128 v[180:183], v197 offset:6656
	ds_read_b128 v[164:167], v197 offset:6688
	v_mfma_f32_32x32x16_bf16 v[0:15], v[80:83], v[230:233], v[0:15]
	ds_read_b128 v[156:159], v197 offset:64
	ds_read_b128 v[140:143], v197 offset:96
	v_exp_f32_e32 v48, v48
	v_exp_f32_e32 v49, v49
	v_exp_f32_e32 v50, v50
	v_add_f32_e32 v195, v48, v49
	v_exp_f32_e32 v51, v51
	v_mfma_f32_32x32x16_bf16 v[0:15], v[84:87], v[238:241], v[0:15]
	s_setprio 0
	ds_read_b128 v[176:179], v197 offset:6720
	ds_read_b128 v[160:163], v197 offset:6752
	v_add_f32_e32 v195, v50, v195
	v_exp_f32_e32 v52, v52
	v_add_f32_e32 v195, v51, v195
	v_exp_f32_e32 v53, v53
	v_add_f32_e32 v195, v52, v195
	v_exp_f32_e32 v54, v54
	v_mfma_f32_32x32x16_bf16 v[16:31], v[64:67], v[214:217], v[16:31]
	ds_read_b128 v[148:151], v197 offset:128
	ds_read_b128 v[136:139], v197 offset:160
	v_add_f32_e32 v195, v53, v195
	v_exp_f32_e32 v55, v55
	v_add_f32_e32 v195, v54, v195
	v_exp_f32_e32 v56, v56
	v_add_f32_e32 v195, v55, v195
	v_exp_f32_e32 v57, v57
	v_add_f32_e32 v195, v56, v195
	v_mfma_f32_32x32x16_bf16 v[16:31], v[68:71], v[218:221], v[16:31]
	ds_read_b128 v[168:171], v197 offset:6784
	ds_read_b128 v[144:147], v197 offset:6816
	v_exp_f32_e32 v58, v58
	v_add_f32_e32 v195, v57, v195
	v_exp_f32_e32 v59, v59
	v_add_f32_e32 v195, v58, v195
	v_exp_f32_e32 v60, v60
	v_add_f32_e32 v195, v59, v195
	v_mfma_f32_32x32x16_bf16 v[16:31], v[80:83], v[226:229], v[16:31]
	v_exp_f32_e32 v61, v61
	v_add_f32_e32 v195, v60, v195
	v_exp_f32_e32 v62, v62
	v_add_f32_e32 v195, v61, v195
	v_exp_f32_e32 v63, v63
	v_add_f32_e32 v195, v62, v195
	v_mfma_f32_32x32x16_bf16 v[16:31], v[84:87], v[234:237], v[16:31]
	v_add_f32_e32 v195, v63, v195
	v_cvt_pk_bf16_f32 v48, v48, v49
	v_cvt_pk_bf16_f32 v49, v50, v51
	v_cvt_pk_bf16_f32 v50, v52, v53
	v_cvt_pk_bf16_f32 v51, v54, v55
	v_cvt_pk_bf16_f32 v52, v56, v57
	v_cvt_pk_bf16_f32 v53, v58, v59
	v_cvt_pk_bf16_f32 v54, v60, v61
	v_cvt_pk_bf16_f32 v55, v62, v63
	s_branch .LatA_ctl

.LBB0_1103:
	s_or_b64 exec, exec, s[4:5]
	v_and_b32_e32 v2, 0x60, v190
	s_movk_i32 s4, 0x90
	v_lshlrev_b32_e32 v1, 3, v24
	v_mad_u32_u24 v208, v207, s4, 0
	v_mad_u64_u32 v[2:3], s[4:5], v20, s4, v[2:3]
	v_and_or_b32 v1, v1, 8, v2
	v_lshlrev_b32_e32 v2, 6, v207
	v_add_u32_e32 v210, 0, v1
	v_add3_u32 v209, v208, v2, v184
	v_add_u32_e32 v0, 0, v0
	v_add_u32_e32 v211, 0x9800, v210
	s_waitcnt vmcnt(3)
	ds_write_b128 v0, v[4:7] offset:13312
	s_waitcnt vmcnt(2)
	ds_write2_b64 v211, v[8:9], v[10:11] offset0:128 offset1:130
	s_waitcnt lgkmcnt(0)
	s_barrier
	ds_read_b128 v[0:3], v209
	ds_read_b128 v[4:7], v209 offset:32
	ds_read_b128 v[8:11], v209 offset:6656
	ds_read_b128 v[12:15], v209 offset:6688
	ds_read_b128 v[16:19], v209 offset:64
	ds_read_b128 v[20:23], v209 offset:96
	ds_read_b128 v[24:27], v209 offset:6720
	ds_read_b128 v[28:31], v209 offset:6752
	ds_read_b128 v[64:67], v209 offset:128
	ds_read_b128 v[68:71], v209 offset:160
	ds_read_b128 v[72:75], v209 offset:6784
	ds_read_b128 v[76:79], v209 offset:6816
	s_mov_b32 s90, 2
	s_lshl_b32 s69, s68, 2
	s_mov_b32 s40, 0
	s_cmp_eq_u32 s68, 0
	s_waitcnt lgkmcnt(11)
	v_mfma_f32_32x32x16_bf16 v[48:63], v[0:3], v[100:103], 0
	s_waitcnt lgkmcnt(9)
	v_mfma_f32_32x32x16_bf16 v[32:47], v[8:11], v[100:103], 0
	v_mfma_f32_32x32x16_bf16 v[48:63], v[4:7], v[104:107], v[48:63]
	s_waitcnt lgkmcnt(8)
	v_mfma_f32_32x32x16_bf16 v[32:47], v[12:15], v[104:107], v[32:47]
	s_waitcnt lgkmcnt(7)
	v_mfma_f32_32x32x16_bf16 v[48:63], v[16:19], v[108:111], v[48:63]
	s_waitcnt lgkmcnt(5)
	v_mfma_f32_32x32x16_bf16 v[32:47], v[24:27], v[108:111], v[32:47]
	v_mfma_f32_32x32x16_bf16 v[48:63], v[20:23], v[112:115], v[48:63]
	s_waitcnt lgkmcnt(4)
	v_mfma_f32_32x32x16_bf16 v[32:47], v[28:31], v[112:115], v[32:47]
	s_waitcnt lgkmcnt(3)
	v_mfma_f32_32x32x16_bf16 v[48:63], v[64:67], v[116:119], v[48:63]
	s_waitcnt lgkmcnt(1)
	v_mfma_f32_32x32x16_bf16 v[32:47], v[72:75], v[116:119], v[32:47]
	v_mfma_f32_32x32x16_bf16 v[48:63], v[68:71], v[120:123], v[48:63]
	s_waitcnt lgkmcnt(0)
	v_mfma_f32_32x32x16_bf16 v[32:47], v[76:79], v[120:123], v[32:47]
	s_cbranch_scc1 .LBB0_1114
	ds_read_b128 v[172:175], v209 offset:13312
	ds_read_b128 v[152:155], v209 offset:13344
	ds_read_b128 v[180:183], v209 offset:19968
	ds_read_b128 v[164:167], v209 offset:20000
	ds_read_b128 v[156:159], v209 offset:13376
	ds_read_b128 v[140:143], v209 offset:13408
	ds_read_b128 v[176:179], v209 offset:20032
	ds_read_b128 v[160:163], v209 offset:20064
	ds_read_b128 v[148:151], v209 offset:13440
	ds_read_b128 v[136:139], v209 offset:13472
	ds_read_b128 v[168:171], v209 offset:20096
	ds_read_b128 v[144:147], v209 offset:20128
	v_lshl_add_u64 v[0:1], s[60:61], 0, v[192:193]
	v_mov_b32_e32 v191, v97
	v_mov_b32_e32 v198, 0
	v_lshl_add_u64 v[98:99], s[96:97], 0, v[186:187]
	v_lshl_add_u64 v[202:203], s[96:97], 0, v[188:189]
	v_lshl_add_u64 v[204:205], v[0:1], 0, v[190:191]
	s_add_u32 s98, s94, 0x12209000
	s_addc_u32 s99, s95, 0
	s_add_u32 s100, s94, 0x11200000
	s_addc_u32 s101, s95, 0

	v_exp_f32_e32 v48, v48
	v_exp_f32_e32 v49, v49
	v_exp_f32_e32 v50, v50
	v_add_f32_e32 v195, v48, v49
	v_exp_f32_e32 v51, v51
	v_add_f32_e32 v195, v50, v195
	v_exp_f32_e32 v52, v52
	v_add_f32_e32 v195, v51, v195
	v_exp_f32_e32 v53, v53
	v_add_f32_e32 v195, v52, v195
	v_exp_f32_e32 v54, v54
	v_add_f32_e32 v195, v53, v195
	v_exp_f32_e32 v55, v55
	v_add_f32_e32 v195, v54, v195
	v_exp_f32_e32 v56, v56
	v_add_f32_e32 v195, v55, v195
	v_exp_f32_e32 v57, v57
	v_add_f32_e32 v195, v56, v195
	v_exp_f32_e32 v58, v58
	v_add_f32_e32 v195, v57, v195
	v_exp_f32_e32 v59, v59
	v_add_f32_e32 v195, v58, v195
	v_exp_f32_e32 v60, v60
	v_add_f32_e32 v195, v59, v195
	v_exp_f32_e32 v61, v61
	v_add_f32_e32 v195, v60, v195
	v_exp_f32_e32 v62, v62
	v_add_f32_e32 v195, v61, v195
	v_exp_f32_e32 v63, v63
	v_add_f32_e32 v195, v62, v195
	v_add_f32_e32 v195, v63, v195
	v_cvt_pk_bf16_f32 v48, v48, v49
	v_cvt_pk_bf16_f32 v49, v50, v51
	v_cvt_pk_bf16_f32 v50, v52, v53
	v_cvt_pk_bf16_f32 v51, v54, v55
	v_cvt_pk_bf16_f32 v52, v56, v57
	v_cvt_pk_bf16_f32 v53, v58, v59
	v_cvt_pk_bf16_f32 v54, v60, v61
	v_cvt_pk_bf16_f32 v55, v62, v63
	v_mov_b32_e32 v0, 0
	v_mov_b32_e32 v1, v198
	v_mov_b32_e32 v2, v198
	v_mov_b32_e32 v3, v198
	v_mov_b32_e32 v4, v198
	v_mov_b32_e32 v5, v198
	v_mov_b32_e32 v6, v198
	v_mov_b32_e32 v7, v198
	v_mov_b32_e32 v8, v198
	v_mov_b32_e32 v9, v198
	v_mov_b32_e32 v10, v198
	v_mov_b32_e32 v11, v198
	v_mov_b32_e32 v12, v198
	v_mov_b32_e32 v13, v198
	v_mov_b32_e32 v14, v198
	v_mov_b32_e32 v15, v198
	v_mov_b32_e32 v16, 0
	v_mov_b32_e32 v17, v198
	v_mov_b32_e32 v18, v198
	v_mov_b32_e32 v19, v198
	v_mov_b32_e32 v20, v198
	v_mov_b32_e32 v21, v198
	v_mov_b32_e32 v22, v198
	v_mov_b32_e32 v23, v198
	v_mov_b32_e32 v24, v198
	v_mov_b32_e32 v25, v198
	v_mov_b32_e32 v26, v198
	v_mov_b32_e32 v27, v198
	v_mov_b32_e32 v28, v198
	v_mov_b32_e32 v29, v198
	v_mov_b32_e32 v30, v198
	v_mov_b32_e32 v31, v198
	s_mov_b32 s41, 0x2c000
	s_branch .LBB0_1106
.LBB0_1106:
	s_waitcnt lgkmcnt(11)
	v_mfma_f32_32x32x16_bf16 v[64:79], v[172:175], v[100:103], 0
	v_exp_f32_e32 v32, v32
	v_exp_f32_e32 v33, v33
	s_waitcnt lgkmcnt(9)
	v_mfma_f32_32x32x16_bf16 v[80:95], v[180:183], v[100:103], 0
	v_exp_f32_e32 v34, v34
	v_add_f32_e32 v251, v32, v33
	v_exp_f32_e32 v35, v35
	v_add_f32_e32 v251, v34, v251
	v_mfma_f32_32x32x16_bf16 v[64:79], v[152:155], v[104:107], v[64:79]
	v_exp_f32_e32 v36, v36
	v_add_f32_e32 v251, v35, v251
	v_exp_f32_e32 v37, v37
	s_waitcnt lgkmcnt(8)
	v_mfma_f32_32x32x16_bf16 v[80:95], v[164:167], v[104:107], v[80:95]
	v_add_f32_e32 v251, v36, v251
	v_exp_f32_e32 v38, v38
	v_add_f32_e32 v251, v37, v251
	s_waitcnt lgkmcnt(7)
	v_mfma_f32_32x32x16_bf16 v[64:79], v[156:159], v[108:111], v[64:79]
	v_exp_f32_e32 v39, v39
	v_add_f32_e32 v251, v38, v251
	v_exp_f32_e32 v40, v40
	s_mul_i32 s6, s90, 0x3400
	s_add_i32 s7, s6, 0

	v_add_u32_e32 v253, s7, v96
	s_waitcnt vmcnt(1)
	ds_write_b128 v253, v[128:131]
	s_and_saveexec_b64 s[4:5], s[2:3]
	v_add_u32_e32 v253, s7, v185
	ds_write_b128 v253, v[124:127]
	s_or_b64 exec, exec, s[4:5]
	v_lshl_add_u64 v[200:201], s[100:101], 0, v[204:205]

	v_add_u32_e32 v254, 0xc000, v210
	v_lshl_add_u64 v[128:129], s[98:99], 0, v[98:99]
	s_nop 0
	global_load_dwordx4 v[128:131], v[128:129], off
	s_waitcnt vmcnt(1)
	ds_write2_b64 v254, v[132:133], v[134:135] offset1:2

	s_and_saveexec_b64 s[4:5], s[2:3]
	s_cbranch_execz .LatB_h0
	v_lshl_add_u64 v[124:125], s[98:99], 0, v[202:203]
	s_nop 0
	global_load_dwordx4 v[124:127], v[124:125], off
.LatB_h0:
	s_or_b64 exec, exec, s[4:5]
	global_load_dwordx4 v[132:135], v[200:201], off offset:256

	s_waitcnt lgkmcnt(7)
	v_mfma_f32_32x32x16_bf16 v[80:95], v[176:179], v[108:111], v[80:95]
	v_add_f32_e32 v251, v39, v251
	v_exp_f32_e32 v41, v41
	v_add_f32_e32 v251, v40, v251
	v_mfma_f32_32x32x16_bf16 v[64:79], v[140:143], v[112:115], v[64:79]
	v_exp_f32_e32 v42, v42
	v_add_f32_e32 v251, v41, v251
	v_exp_f32_e32 v43, v43
	s_waitcnt lgkmcnt(6)
	v_mfma_f32_32x32x16_bf16 v[80:95], v[160:163], v[112:115], v[80:95]
	v_add_f32_e32 v251, v42, v251
	v_exp_f32_e32 v44, v44
	v_add_f32_e32 v251, v43, v251
	v_exp_f32_e32 v45, v45
	s_waitcnt lgkmcnt(5)
	v_mfma_f32_32x32x16_bf16 v[64:79], v[148:151], v[116:119], v[64:79]
	v_add_f32_e32 v251, v44, v251
	v_exp_f32_e32 v46, v46
	v_add_f32_e32 v251, v45, v251
	v_add_u32_e32 v196, v208, v184
	ds_read_b128 v[212:215], v196 offset:44544
	ds_read_b128 v[216:219], v196 offset:39936
	ds_read_b128 v[220:223], v196 offset:39968
	ds_read_b128 v[224:227], v196 offset:44576
	ds_read_b128 v[228:231], v196 offset:40000
	ds_read_b128 v[232:235], v196 offset:44608
	ds_read_b128 v[236:239], v196 offset:40032
	ds_read_b128 v[240:243], v196 offset:44640
	s_waitcnt lgkmcnt(11)
	v_mfma_f32_32x32x16_bf16 v[80:95], v[168:171], v[116:119], v[80:95]
	v_exp_f32_e32 v47, v47
	v_add_f32_e32 v251, v46, v251
	v_add_f32_e32 v251, v47, v251
	v_cvt_pk_bf16_f32 v32, v32, v33
	v_mfma_f32_32x32x16_bf16 v[64:79], v[136:139], v[120:123], v[64:79]
	v_cvt_pk_bf16_f32 v33, v34, v35
	v_cvt_pk_bf16_f32 v34, v36, v37
	v_cvt_pk_bf16_f32 v35, v38, v39
	v_cvt_pk_bf16_f32 v36, v40, v41
	s_waitcnt lgkmcnt(10)
	v_mfma_f32_32x32x16_bf16 v[80:95], v[144:147], v[120:123], v[80:95]
	v_cvt_pk_bf16_f32 v37, v42, v43
	v_cvt_pk_bf16_f32 v38, v44, v45
	v_cvt_pk_bf16_f32 v39, v46, v47
	v_add_f32_e32 v195, v195, v251
	v_add_f32_e32 v198, v198, v195
	s_waitcnt lgkmcnt(0)
	s_barrier

	v_add_u32_e32 v197, s6, v209
	s_setprio 1
	v_mfma_f32_32x32x16_bf16 v[0:15], v[48:51], v[212:215], v[0:15]
	ds_read_b128 v[172:175], v197
	ds_read_b128 v[152:155], v197 offset:32
	v_mfma_f32_32x32x16_bf16 v[0:15], v[52:55], v[224:227], v[0:15]
	ds_read_b128 v[180:183], v197 offset:6656
	ds_read_b128 v[164:167], v197 offset:6688
	v_mfma_f32_32x32x16_bf16 v[0:15], v[32:35], v[232:235], v[0:15]
	ds_read_b128 v[156:159], v197 offset:64
	ds_read_b128 v[140:143], v197 offset:96
	v_exp_f32_e32 v64, v64
	v_exp_f32_e32 v65, v65
	v_exp_f32_e32 v66, v66
	v_add_f32_e32 v195, v64, v65
	v_exp_f32_e32 v67, v67
	v_mfma_f32_32x32x16_bf16 v[0:15], v[36:39], v[240:243], v[0:15]
	s_setprio 0
	ds_read_b128 v[176:179], v197 offset:6720
	ds_read_b128 v[160:163], v197 offset:6752
	v_add_f32_e32 v195, v66, v195
	v_exp_f32_e32 v68, v68
	v_add_f32_e32 v195, v67, v195
	v_exp_f32_e32 v69, v69
	v_add_f32_e32 v195, v68, v195
	v_exp_f32_e32 v70, v70
	v_mfma_f32_32x32x16_bf16 v[16:31], v[48:51], v[216:219], v[16:31]
	ds_read_b128 v[148:151], v197 offset:128
	ds_read_b128 v[136:139], v197 offset:160
	v_add_f32_e32 v195, v69, v195
	v_exp_f32_e32 v71, v71
	v_add_f32_e32 v195, v70, v195
	v_exp_f32_e32 v72, v72
	v_add_f32_e32 v195, v71, v195
	v_exp_f32_e32 v73, v73
	v_add_f32_e32 v195, v72, v195
	v_mfma_f32_32x32x16_bf16 v[16:31], v[52:55], v[220:223], v[16:31]
	ds_read_b128 v[168:171], v197 offset:6784
	ds_read_b128 v[144:147], v197 offset:6816
	v_exp_f32_e32 v74, v74
	v_add_f32_e32 v195, v73, v195
	v_exp_f32_e32 v75, v75
	v_add_f32_e32 v195, v74, v195
	v_exp_f32_e32 v76, v76
	v_add_f32_e32 v195, v75, v195
	v_mfma_f32_32x32x16_bf16 v[16:31], v[32:35], v[228:231], v[16:31]
	v_exp_f32_e32 v77, v77
	v_add_f32_e32 v195, v76, v195
	v_exp_f32_e32 v78, v78
	v_add_f32_e32 v195, v77, v195
	v_exp_f32_e32 v79, v79
	v_add_f32_e32 v195, v78, v195
	v_mfma_f32_32x32x16_bf16 v[16:31], v[36:39], v[236:239], v[16:31]
	v_add_f32_e32 v195, v79, v195
	v_cvt_pk_bf16_f32 v64, v64, v65
	v_cvt_pk_bf16_f32 v65, v66, v67
	v_cvt_pk_bf16_f32 v66, v68, v69
	v_cvt_pk_bf16_f32 v67, v70, v71
	v_cvt_pk_bf16_f32 v68, v72, v73
	v_cvt_pk_bf16_f32 v69, v74, v75
	v_cvt_pk_bf16_f32 v70, v76, v77
	v_cvt_pk_bf16_f32 v71, v78, v79
	s_waitcnt lgkmcnt(11)
	v_mfma_f32_32x32x16_bf16 v[48:63], v[172:175], v[100:103], 0
	v_exp_f32_e32 v80, v80
	v_exp_f32_e32 v81, v81
	s_waitcnt lgkmcnt(9)
	v_mfma_f32_32x32x16_bf16 v[32:47], v[180:183], v[100:103], 0
	v_exp_f32_e32 v82, v82
	v_add_f32_e32 v251, v80, v81
	v_exp_f32_e32 v83, v83
	v_add_f32_e32 v251, v82, v251
	v_mfma_f32_32x32x16_bf16 v[48:63], v[152:155], v[104:107], v[48:63]
	v_exp_f32_e32 v84, v84
	v_add_f32_e32 v251, v83, v251
	v_exp_f32_e32 v85, v85
	s_waitcnt lgkmcnt(8)
	v_mfma_f32_32x32x16_bf16 v[32:47], v[164:167], v[104:107], v[32:47]
	v_add_f32_e32 v251, v84, v251
	v_exp_f32_e32 v86, v86
	v_add_f32_e32 v251, v85, v251
	s_waitcnt lgkmcnt(7)
	v_mfma_f32_32x32x16_bf16 v[48:63], v[156:159], v[108:111], v[48:63]
	v_exp_f32_e32 v87, v87
	v_add_f32_e32 v251, v86, v251
	v_exp_f32_e32 v88, v88
	s_add_i32 s4, s90, 1
	s_cmp_lg_u32 s90, 2
	s_cselect_b32 s68, s4, 0
	s_mul_i32 s6, s68, 0x3400
	s_add_i32 s7, s6, 0
	s_add_u32 s98, s98, 0x3000
	s_addc_u32 s99, s99, 0

	v_add_u32_e32 v253, s7, v96
	s_waitcnt vmcnt(1)
	ds_write_b128 v253, v[128:131]
	s_and_saveexec_b64 s[4:5], s[2:3]
	v_add_u32_e32 v253, s7, v185
	ds_write_b128 v253, v[124:127]
	s_or_b64 exec, exec, s[4:5]
	v_lshl_add_u64 v[200:201], s[100:101], 0, v[204:205]

	s_waitcnt vmcnt(0)
	ds_write2_b64 v211, v[132:133], v[134:135] offset0:128 offset1:130
	v_lshl_add_u64 v[128:129], s[98:99], 0, v[98:99]
	s_nop 0
	global_load_dwordx4 v[128:131], v[128:129], off

	s_and_saveexec_b64 s[4:5], s[2:3]
	s_cbranch_execz .LatB_h1
	v_lshl_add_u64 v[124:125], s[98:99], 0, v[202:203]
	s_nop 0
	global_load_dwordx4 v[124:127], v[124:125], off
.LatB_h1:
	s_or_b64 exec, exec, s[4:5]
	global_load_dwordx4 v[132:135], v[200:201], off offset:384

	s_sub_u32 s98, s98, 0x3000
	s_subb_u32 s99, s99, 0

	s_waitcnt lgkmcnt(7)
	v_mfma_f32_32x32x16_bf16 v[32:47], v[176:179], v[108:111], v[32:47]
	v_add_f32_e32 v251, v87, v251
	v_exp_f32_e32 v89, v89
	v_add_f32_e32 v251, v88, v251
	v_mfma_f32_32x32x16_bf16 v[48:63], v[140:143], v[112:115], v[48:63]
	v_exp_f32_e32 v90, v90
	v_add_f32_e32 v251, v89, v251
	v_exp_f32_e32 v91, v91
	s_waitcnt lgkmcnt(6)
	v_mfma_f32_32x32x16_bf16 v[32:47], v[160:163], v[112:115], v[32:47]
	v_add_f32_e32 v251, v90, v251
	v_exp_f32_e32 v92, v92
	v_add_f32_e32 v251, v91, v251
	v_exp_f32_e32 v93, v93
	s_waitcnt lgkmcnt(5)
	v_mfma_f32_32x32x16_bf16 v[48:63], v[148:151], v[116:119], v[48:63]
	v_add_f32_e32 v251, v92, v251
	v_exp_f32_e32 v94, v94
	v_add_f32_e32 v251, v93, v251
	v_add_u32_e32 v196, v208, v184
	ds_read_b128 v[212:215], v196 offset:53760
	ds_read_b128 v[216:219], v196 offset:49152
	ds_read_b128 v[220:223], v196 offset:49184
	ds_read_b128 v[224:227], v196 offset:53792
	ds_read_b128 v[228:231], v196 offset:49216
	ds_read_b128 v[232:235], v196 offset:53824
	ds_read_b128 v[236:239], v196 offset:49248
	ds_read_b128 v[240:243], v196 offset:53856
	s_waitcnt lgkmcnt(11)
	v_mfma_f32_32x32x16_bf16 v[32:47], v[168:171], v[116:119], v[32:47]
	v_exp_f32_e32 v95, v95
	v_add_f32_e32 v251, v94, v251
	v_add_f32_e32 v251, v95, v251
	v_cvt_pk_bf16_f32 v80, v80, v81
	v_mfma_f32_32x32x16_bf16 v[48:63], v[136:139], v[120:123], v[48:63]
	v_cvt_pk_bf16_f32 v81, v82, v83
	v_cvt_pk_bf16_f32 v82, v84, v85
	v_cvt_pk_bf16_f32 v83, v86, v87
	v_cvt_pk_bf16_f32 v84, v88, v89
	s_waitcnt lgkmcnt(10)
	v_mfma_f32_32x32x16_bf16 v[32:47], v[144:147], v[120:123], v[32:47]
	v_cvt_pk_bf16_f32 v85, v90, v91
	v_cvt_pk_bf16_f32 v86, v92, v93
	v_cvt_pk_bf16_f32 v87, v94, v95
	v_add_f32_e32 v195, v195, v251
	v_add_f32_e32 v198, v198, v195
	s_add_i32 s40, s40, 2
	s_waitcnt lgkmcnt(0)
	s_barrier

	s_cmp_ge_u32 s40, s69
	s_cbranch_scc1 .LatB_yplain

	v_add_u32_e32 v197, s6, v209
	s_setprio 1
	v_mfma_f32_32x32x16_bf16 v[0:15], v[64:67], v[212:215], v[0:15]
	ds_read_b128 v[172:175], v197
	ds_read_b128 v[152:155], v197 offset:32
	v_mfma_f32_32x32x16_bf16 v[0:15], v[68:71], v[224:227], v[0:15]
	ds_read_b128 v[180:183], v197 offset:6656
	ds_read_b128 v[164:167], v197 offset:6688
	v_mfma_f32_32x32x16_bf16 v[0:15], v[80:83], v[232:235], v[0:15]
	ds_read_b128 v[156:159], v197 offset:64
	ds_read_b128 v[140:143], v197 offset:96
	v_exp_f32_e32 v48, v48
	v_exp_f32_e32 v49, v49
	v_exp_f32_e32 v50, v50
	v_add_f32_e32 v195, v48, v49
	v_exp_f32_e32 v51, v51
	v_mfma_f32_32x32x16_bf16 v[0:15], v[84:87], v[240:243], v[0:15]
	s_setprio 0
	ds_read_b128 v[176:179], v197 offset:6720
	ds_read_b128 v[160:163], v197 offset:6752
	v_add_f32_e32 v195, v50, v195
	v_exp_f32_e32 v52, v52
	v_add_f32_e32 v195, v51, v195
	v_exp_f32_e32 v53, v53
	v_add_f32_e32 v195, v52, v195
	v_exp_f32_e32 v54, v54
	v_mfma_f32_32x32x16_bf16 v[16:31], v[64:67], v[216:219], v[16:31]
	ds_read_b128 v[148:151], v197 offset:128
	ds_read_b128 v[136:139], v197 offset:160
	v_add_f32_e32 v195, v53, v195
	v_exp_f32_e32 v55, v55
	v_add_f32_e32 v195, v54, v195
	v_exp_f32_e32 v56, v56
	v_add_f32_e32 v195, v55, v195
	v_exp_f32_e32 v57, v57
	v_add_f32_e32 v195, v56, v195
	v_mfma_f32_32x32x16_bf16 v[16:31], v[68:71], v[220:223], v[16:31]
	ds_read_b128 v[168:171], v197 offset:6784
	ds_read_b128 v[144:147], v197 offset:6816
	v_exp_f32_e32 v58, v58
	v_add_f32_e32 v195, v57, v195
	v_exp_f32_e32 v59, v59
	v_add_f32_e32 v195, v58, v195
	v_exp_f32_e32 v60, v60
	v_add_f32_e32 v195, v59, v195
	v_mfma_f32_32x32x16_bf16 v[16:31], v[80:83], v[228:231], v[16:31]
	v_exp_f32_e32 v61, v61
	v_add_f32_e32 v195, v60, v195
	v_exp_f32_e32 v62, v62
	v_add_f32_e32 v195, v61, v195
	v_exp_f32_e32 v63, v63
	v_add_f32_e32 v195, v62, v195
	v_mfma_f32_32x32x16_bf16 v[16:31], v[84:87], v[236:239], v[16:31]
	v_add_f32_e32 v195, v63, v195
	v_cvt_pk_bf16_f32 v48, v48, v49
	v_cvt_pk_bf16_f32 v49, v50, v51
	v_cvt_pk_bf16_f32 v50, v52, v53
	v_cvt_pk_bf16_f32 v51, v54, v55
	v_cvt_pk_bf16_f32 v52, v56, v57
	v_cvt_pk_bf16_f32 v53, v58, v59
	v_cvt_pk_bf16_f32 v54, v60, v61
	v_cvt_pk_bf16_f32 v55, v62, v63
	s_branch .LatB_ctl
